# v5_4wave
# speedup vs baseline: 1.0275x; 1.0275x over previous
; __device__ __forceinline__ int opaque_tid() { int t = threadIdx.x; asm volatile("" : "+v"(t)); return t; }
; __device__ void gla_scan_item(const Params& p, int id) {
;   const int tid = opaque_tid(), lane = tid & 63, w = tid >> 6, fr = lane & 15, fq = lane >> 4;
;   const int ws = __builtin_amdgcn_readfirstlane(w) & 7;
;   int seq, j;
;   if (id < 32) { seq = 4; j = id; } else { seq = (id - 32) >> 5; j = (id - 32) & 31; }
;   const int h = (j & 7) >> 1, dir = j & 1, vs = (j >> 3) & 3;
;   const int start = seq_start(seq), len = seq_len(seq), nch = len >> 6, chunk0 = start >> 6;
;   const int cfirst = dir ? chunk0 + nch - 1 : chunk0, cstep = dir ? -1 : 1;
;   u16* O = (dir ? p.OB : p.OF) + h * 512 + vs * 128 + 16 * w + 4 * fq;
;   const u16* vt_base = p.VTG + ((size_t)h * 512 + vs * 128 + 16 * w + fr) * 64 + 8 * fq;
;   const char* blob_base = p.BLOBR + (size_t)(h * 2 + dir) * BLOB_BYTES + lane * 16;
;   char* lds_lane = smem + lane * 16;
;     ...
;   f32x4 st[16];
; #pragma unroll
;   for (int T = 0; T < 16; ++T) st[T] = f32x4{0.f, 0.f, 0.f, 0.f};
;   bf16x8 vfA[2], vfB[2];
;   BLOB_DMA(cfirst, 0);
;   VT_LOAD(vfA, cfirst);
;   asm volatile("s_waitcnt vmcnt(0)" ::: "memory");
;   __syncthreads();
; __device__ void phase2(const Params& p, const int rep) {
;     ...
;     for (int it = blockIdx.x; it < 160; it += gridDim.x) gla_scan_item(p, it);
.LBB0_421:
	s_or_b64 exec, exec, s[0:1]
	s_cmpk_gt_i32 s10, 0x13f
	s_barrier
	s_cbranch_scc1 .LBB0_432
	s_mov_b32 s7, 0
	v_mov_b32_e32 v153, 0
	v_mov_b32_e32 v161, 0xa0000
	s_mov_b32 s2, 0x10000
	s_movk_i32 s3, 0xfe70
	s_mov_b32 s11, 0x20000
	s_mov_b32 s88, 0x30000
	s_mov_b32 s89, s10
	s_branch .LBB0_424
.LBB0_423:
	s_addk_i32 s89, 0xc0
	s_cmpk_lt_i32 s89, 0x100
	s_cbranch_scc1 .LBB0_432
	s_cmpk_gt_i32 s89, 0x13f
	s_cbranch_scc1 .LBB0_432
.LBB0_424:
	s_sub_i32 s0, s89, 64
	s_lshr_b32 s0, s0, 6
	s_cmp_gt_i32 s89, 63
	s_cselect_b32 s0, s0, 4
	s_and_b32 s8, s89, 1
	s_lshl_b32 s9, s0, 5
	s_cmp_lt_u32 s0, 4
	v_readlane_b32 s56, v255, 0
	v_mov_b32_e32 v8, v248
	s_cselect_b32 s90, 32, 0x80
	s_and_b32 s0, s89, 7
	v_readlane_b32 s57, v255, 1
	s_add_i32 s28, s9, s90
	v_ashrrev_i32_e32 v3, 6, v8
	s_mul_i32 s0, s0, 0x14000
	s_mov_b64 s[4:5], s[56:57]
	v_readfirstlane_b32 s6, v3
	s_add_u32 s0, s4, s0
	s_addc_u32 s1, s5, 0
	s_and_b32 s66, s6, 7
	s_lshr_b32 s99, s6, 2
	s_add_i32 s28, s28, -1
	v_and_b32_e32 v2, 63, v8
	s_cmp_eq_u32 s8, 0
	s_cselect_b64 s[72:73], -1, 0
	v_lshlrev_b32_e32 v152, 4, v2
	v_lshl_add_u64 v[154:155], s[0:1], 0, v[152:153]
	s_and_b64 s[0:1], s[72:73], exec
	s_cselect_b32 s6, s9, s28
	s_lshl_b32 s28, s66, 10
	v_mad_u64_u32 v[0:1], s[0:1], s6, v161, v[154:155]
	v_or_b32_e32 v6, s28, v152
	s_mov_b32 s29, s7
	v_readfirstlane_b32 s0, v6
	v_or_b32_e32 v7, 0x2000, v6
	v_lshl_add_u64 v[4:5], v[0:1], 0, s[28:29]
	s_mov_b32 m0, s0
	s_or_b32 s30, s28, 0x2000
	s_mov_b32 s31, s7
	v_readfirstlane_b32 s0, v7
	v_or_b32_e32 v7, 0x4000, v6
	global_load_lds_dwordx4 v[4:5], off
	v_lshl_add_u64 v[4:5], v[0:1], 0, s[30:31]
	s_mov_b32 m0, s0
	s_or_b32 s34, s28, 0x4000
	s_mov_b32 s35, s7
	v_readfirstlane_b32 s0, v7
	v_or_b32_e32 v7, 0x6000, v6
	global_load_lds_dwordx4 v[4:5], off
	v_lshl_add_u64 v[4:5], v[0:1], 0, s[34:35]
	s_mov_b32 m0, s0
	s_or_b32 s46, s28, 0x6000
	s_mov_b32 s47, s7
	v_readfirstlane_b32 s0, v7
	v_or_b32_e32 v7, 0x8000, v6
	v_readlane_b32 s58, v255, 2
	v_readlane_b32 s59, v255, 3
	global_load_lds_dwordx4 v[4:5], off
	v_lshl_add_u64 v[4:5], v[0:1], 0, s[46:47]
	s_mov_b32 m0, s0
	s_or_b32 s56, s28, 0x8000
	s_mov_b32 s57, s7
	v_readfirstlane_b32 s0, v7
	v_or_b32_e32 v7, 0xa000, v6
	global_load_lds_dwordx4 v[4:5], off
	v_lshl_add_u64 v[4:5], v[0:1], 0, s[56:57]
	s_mov_b32 m0, s0
	s_or_b32 s58, s28, 0xa000
	s_mov_b32 s59, s7
	v_readfirstlane_b32 s0, v7
	v_or_b32_e32 v7, 0xc000, v6
	global_load_lds_dwordx4 v[4:5], off
	v_lshl_add_u64 v[4:5], v[0:1], 0, s[58:59]
	s_mov_b32 m0, s0
	s_or_b32 s60, s28, 0xc000
	s_mov_b32 s61, s7
	v_readfirstlane_b32 s0, v7
	v_or_b32_e32 v6, 0xe000, v6
	s_or_b32 s64, s28, 0x10000
	global_load_lds_dwordx4 v[4:5], off
	v_lshl_add_u64 v[4:5], v[0:1], 0, s[60:61]
	s_mov_b32 m0, s0
	s_or_b32 s62, s28, 0xe000
	s_mov_b32 s63, s7
	v_readfirstlane_b32 s0, v6
	v_or_b32_e32 v6, s64, v152
	global_load_lds_dwordx4 v[4:5], off
	v_lshl_add_u64 v[4:5], v[0:1], 0, s[62:63]
	s_mov_b32 m0, s0
	s_mov_b32 s65, s7
	v_readfirstlane_b32 s0, v6
	global_load_lds_dwordx4 v[4:5], off
	v_lshl_add_u64 v[4:5], v[0:1], 0, s[64:65]
	s_mov_b32 m0, s0
	s_or_b32 s8, s66, 0x48
	global_load_lds_dwordx4 v[4:5], off
	s_cmpk_lt_u32 s8, 0x4a
	s_cselect_b64 s[0:1], -1, 0
	s_lshl_b32 s66, s8, 10
	s_cmpk_gt_u32 s8, 0x49
	s_mov_b32 s67, s7
	v_add_u32_e32 v162, s66, v152
	s_cbranch_scc1 .LBB0_426
	v_readfirstlane_b32 s8, v162
	v_lshl_add_u64 v[0:1], v[0:1], 0, s[66:67]
	s_mov_b32 m0, s8
	s_nop 0
	global_load_lds_dwordx4 v[0:1], off
.LBB0_426:
	s_and_b64 s[8:9], s[72:73], exec
	s_cselect_b32 s91, 1, -1
	s_cselect_b32 s72, s39, s41
	s_cselect_b32 s73, s38, s40
	s_lshl_b32 s8, s89, 8
	s_and_b32 s84, s8, 0x600
	s_lshl_b32 s8, s89, 3
	s_and_b32 s85, s8, 0x1c0
	v_and_b32_e32 v3, 3, v3
	v_lshlrev_b32_e32 v0, 4, v3
	v_ashrrev_i32_e32 v1, 31, v0
	s_or_b32 s8, s84, s85
	s_mov_b32 s9, s7
	v_lshl_add_u64 v[4:5], v[0:1], 0, s[8:9]
	s_lshl_b32 s8, s84, 1
	v_and_b32_e32 v163, 15, v8
	s_add_u32 s8, s73, s8
	v_or_b32_e32 v4, v4, v163
	s_addc_u32 s9, s72, 0
	s_lshl_b32 s72, s85, 1
	v_lshlrev_b64 v[4:5], 7, v[4:5]
	s_add_u32 s8, s8, s72
	v_lshrrev_b32_e32 v9, 4, v2
	s_addc_u32 s9, s9, 0
	v_lshl_add_u64 v[4:5], s[96:97], 0, v[4:5]
	v_and_b32_e32 v10, 48, v2
	v_mov_b32_e32 v11, v153
	v_lshl_add_u64 v[0:1], v[0:1], 1, s[8:9]
	v_lshlrev_b32_e32 v6, 3, v9
	v_mov_b32_e32 v7, v153
	v_lshl_add_u64 v[158:159], v[4:5], 0, v[10:11]
	s_lshl_b64 s[8:9], s[6:7], 18
	v_lshl_add_u64 v[156:157], v[0:1], 0, v[6:7]
	v_lshl_add_u64 v[0:1], v[158:159], 0, s[8:9]
	global_load_dwordx4 v[4:7], v[0:1], off
	s_nop 0
	global_load_dwordx4 v[0:3], v[0:1], off offset:64
	v_mul_u32_u24_e32 v12, 0x108, v163
	v_and_b32_e32 v13, 7, v8
	v_lshlrev_b32_e32 v12, 1, v12
	v_bitop3_b32 v8, v9, v8, 7 bitop3:0x78
	v_bitop3_b32 v9, v9, v13, 4 bitop3:0x36
	v_add_u32_e32 v164, v12, v10
	v_lshlrev_b32_e32 v13, 7, v163
	v_lshlrev_b32_e32 v9, 4, v9
	v_mad_i32_i24 v12, v163, s3, v12
	v_lshlrev_b32_e32 v8, 4, v8
	s_waitcnt vmcnt(0)
; __device__ __forceinline__ void scan_compute(const char* cur, const bf16x8 (&vf)[2], f32x4 (&st)[16],
;                                              u16* O, const int fr, const int fq) {
;   const u16* QEl = (const u16*)(cur + B_QE) + fr * 264 + 8 * fq;
;   const u16* KETl0 = (const u16*)(cur + B_KET) + fr * 64 + ((fq ^ (fr & 7)) << 3);
;   const u16* KETl1 = (const u16*)(cur + B_KET) + fr * 64 + (((4 + fq) ^ (fr & 7)) << 3);
;   const u16* AMl0 = (const u16*)(cur + B_AM) + fr * 64 + ((fq ^ (fr & 7)) << 3);
;   const u16* AMl1 = (const u16*)(cur + B_AM) + fr * 64 + (((4 + fq) ^ (fr & 7)) << 3);
;   const float* EBLl = (const float*)(cur + B_EBL) + 4 * fq;
;     ...
;   {
;     f32x4 oacc[4];
;     u32x4 qf[3][4];
;     bf16x8 af[2][4];
; #pragma unroll
;     for (int qt = 0; qt < 4; ++qt) oacc[qt] = f32x4{0.f, 0.f, 0.f, 0.f};
;     LOADQ(0, 0);
;     LOADQ(1, 1);
; #pragma unroll
;     for (int s = 0; s < 8; ++s) {
;       if (s < 6) { LOADQ((s + 2) % 3, s + 2); }
;       else if (s == 6) {
; #pragma unroll
;         for (int qt = 0; qt < 4; ++qt) af[0][qt] = *(const bf16x8*)(AMl0 + (16 * qt) * 64);
;       } else {
; #pragma unroll
;         for (int qt = 0; qt < 4; ++qt) af[1][qt] = *(const bf16x8*)(AMl1 + (16 * qt) * 64);
;       }
;       u32x4 sw;
;       sw[0] = pack2(st[2 * s][0], st[2 * s][1]);
;       sw[1] = pack2(st[2 * s][2], st[2 * s][3]);
;       sw[2] = pack2(st[2 * s + 1][0], st[2 * s + 1][1]);
; __device__ void gla_scan_item(const Params& p, int id) {
;     ...
;   f32x4 st[16];
; #pragma unroll
;   for (int T = 0; T < 16; ++T) st[T] = f32x4{0.f, 0.f, 0.f, 0.f};
;   bf16x8 vfA[2], vfB[2];
;   BLOB_DMA(cfirst, 0);
;   VT_LOAD(vfA, cfirst);
;   asm volatile("s_waitcnt vmcnt(0)" ::: "memory");
;   __syncthreads();
; #pragma unroll 1
;   for (int n = 0; n < nch; n += 2) {
;     const int nc0 = cfirst + cstep * n, nc1 = nc0 + cstep;
;     const int nc2 = (n + 2 < nch) ? nc1 + cstep : nc1;
;     BLOB_DMA(nc1, BLOB_BYTES);
;     VT_LOAD(vfB, nc1);
;     __builtin_amdgcn_sched_barrier(0);
;     scan_compute(smem, vfA, st, O + (size_t)(nc0 * 64 + fr) * 2048, fr, fq);
;     asm volatile("s_waitcnt vmcnt(0)" ::: "memory");
;     __syncthreads();
;     BLOB_DMA(nc2, 0);
;     VT_LOAD(vfA, nc2);
;     __builtin_amdgcn_sched_barrier(0);
;     scan_compute(smem + BLOB_BYTES, vfB, st, O + (size_t)(nc1 * 64 + fr) * 2048, fr, fq);
	v_add_u32_e32 v14, 0x10400, v13
	v_add_u32_e32 v166, v12, v9
	v_add_u32_e32 v168, v12, v8
	v_add_u32_e32 v12, 0x24400, v13
	v_add_u32_e32 v13, 0x1c400, v13
	v_or_b32_e32 v11, 0x14000, v152
	v_or_b32_e32 v167, v14, v8
	v_or_b32_e32 v173, v12, v8
	v_or_b32_e32 v174, v13, v8
	v_mov_b32_e32 v16, 0
	v_cndmask_b32_e64 v8, 0, 1, s[0:1]
	v_add_u32_e32 v186, s28, v152
	v_or_b32_e32 v165, v14, v9
	v_or_b32_e32 v169, 0x12400, v10
	v_add_u32_e32 v170, 0x14000, v164
	v_or_b32_e32 v171, v12, v9
	v_or_b32_e32 v172, v13, v9
	v_or_b32_e32 v175, 0x26400, v10
	s_lshl_b32 s92, s6, 6
	s_lshl_b32 s93, s91, 7
	v_lshl_or_b32 v176, s91, 6, v163
	s_add_i32 s72, s6, s91
	s_lshl_b32 s6, s91, 1
	s_mov_b32 s94, 2
	v_add_u32_e32 v177, s28, v11
	v_add_u32_e32 v178, s30, v11
	v_add_u32_e32 v179, s34, v11
	v_add_u32_e32 v180, s46, v11
	v_add_u32_e32 v181, s56, v11
	v_add_u32_e32 v182, s58, v11
	v_add_u32_e32 v183, s60, v11
	v_add_u32_e32 v184, s62, v11
	v_add_u32_e32 v185, s64, v11
	v_add_u32_e32 v187, 0x2000, v186
	v_or_b32_e32 v188, 0x4000, v186
	v_add_u32_e32 v189, 0x6000, v186
	v_or_b32_e32 v190, 0x8000, v186
	v_add_u32_e32 v191, 0xa000, v186
	v_or_b32_e32 v192, 0xc000, v186
	v_add_u32_e32 v193, 0xe000, v186
	v_add_u32_e32 v152, s64, v152
	v_cmp_ne_u32_e64 s[0:1], 1, v8
	v_add_u32_e32 v194, s66, v11
	v_mov_b32_e32 v17, v16
	v_mov_b32_e32 v18, v16
	v_mov_b32_e32 v19, v16
	v_mov_b32_e32 v68, v16
	v_mov_b32_e32 v69, v16
	v_mov_b32_e32 v70, v16
	v_mov_b32_e32 v71, v16
	v_mov_b32_e32 v76, v16
	v_mov_b32_e32 v77, v16
	v_mov_b32_e32 v78, v16
	v_mov_b32_e32 v79, v16
	v_mov_b32_e32 v72, v16
	v_mov_b32_e32 v73, v16
	v_mov_b32_e32 v74, v16
	v_mov_b32_e32 v75, v16
	v_mov_b32_e32 v56, v16
	v_mov_b32_e32 v57, v16
	v_mov_b32_e32 v58, v16
	v_mov_b32_e32 v59, v16
	v_mov_b32_e32 v52, v16
	v_mov_b32_e32 v53, v16
	v_mov_b32_e32 v54, v16
	v_mov_b32_e32 v55, v16
	v_mov_b32_e32 v64, v16
	v_mov_b32_e32 v65, v16
	v_mov_b32_e32 v66, v16
	v_mov_b32_e32 v67, v16
	v_mov_b32_e32 v60, v16
	v_mov_b32_e32 v61, v16
	v_mov_b32_e32 v62, v16
	v_mov_b32_e32 v63, v16
	v_mov_b32_e32 v48, v16
	v_mov_b32_e32 v49, v16
	v_mov_b32_e32 v50, v16
	v_mov_b32_e32 v51, v16
	v_mov_b32_e32 v44, v16
	v_mov_b32_e32 v45, v16
	v_mov_b32_e32 v46, v16
	v_mov_b32_e32 v47, v16
	v_mov_b32_e32 v40, v16
	v_mov_b32_e32 v41, v16
	v_mov_b32_e32 v42, v16
	v_mov_b32_e32 v43, v16
	v_mov_b32_e32 v36, v16
	v_mov_b32_e32 v37, v16
	v_mov_b32_e32 v38, v16
	v_mov_b32_e32 v39, v16
	v_mov_b32_e32 v32, v16
	v_mov_b32_e32 v33, v16
	v_mov_b32_e32 v34, v16
	v_mov_b32_e32 v35, v16
	v_mov_b32_e32 v28, v16
	v_mov_b32_e32 v29, v16
	v_mov_b32_e32 v30, v16
	v_mov_b32_e32 v31, v16
	v_mov_b32_e32 v24, v16
	v_mov_b32_e32 v25, v16
	v_mov_b32_e32 v26, v16
	v_mov_b32_e32 v27, v16
	v_mov_b32_e32 v20, v16
	v_mov_b32_e32 v21, v16
	v_mov_b32_e32 v22, v16
	v_mov_b32_e32 v23, v16
	s_waitcnt vmcnt(0) lgkmcnt(0)
	s_barrier
	s_branch .LBB0_428
.LBB0_427:
	s_ashr_i32 s87, s86, 31
	s_lshl_b64 s[8:9], s[86:87], 18
	v_lshl_add_u64 v[0:1], v[158:159], 0, s[8:9]
	global_load_dwordx4 v[4:7], v[0:1], off
	s_nop 0
	global_load_dwordx4 v[0:3], v[0:1], off offset:64
	s_cmp_lg_u32 s99, 0
	s_cbranch_scc1 .Lsc_skipB
	v_pk_mul_f32 v[74:75], v[94:95], v[34:35]
	v_pk_mul_f32 v[72:73], v[92:93], v[32:33]
	v_pk_mul_f32 v[78:79], v[90:91], v[30:31]
	v_pk_mul_f32 v[76:77], v[88:89], v[28:29]
	v_pk_mul_f32 v[30:31], v[102:103], v[42:43]
	v_pk_mul_f32 v[28:29], v[100:101], v[40:41]
	v_pk_mul_f32 v[34:35], v[98:99], v[38:39]
	v_pk_mul_f32 v[32:33], v[96:97], v[36:37]
	v_pk_mul_f32 v[38:39], v[26:27], v[50:51]
	v_pk_mul_f32 v[36:37], v[24:25], v[48:49]
	v_pk_mul_f32 v[42:43], v[22:23], v[46:47]
	v_pk_mul_f32 v[40:41], v[20:21], v[44:45]
	v_pk_mul_f32 v[46:47], v[118:119], v[66:67]
	v_pk_mul_f32 v[44:45], v[116:117], v[64:65]
	v_pk_mul_f32 v[50:51], v[114:115], v[62:63]
	v_pk_mul_f32 v[48:49], v[112:113], v[60:61]
	v_pk_mul_f32 v[62:63], v[126:127], v[58:59]
	v_pk_mul_f32 v[60:61], v[124:125], v[56:57]
	v_pk_mul_f32 v[66:67], v[122:123], v[54:55]
	v_pk_mul_f32 v[64:65], v[120:121], v[52:53]
	v_pk_mul_f32 v[54:55], v[134:135], v[150:151]
	v_pk_mul_f32 v[52:53], v[132:133], v[148:149]
	v_pk_mul_f32 v[58:59], v[130:131], v[146:147]
	v_pk_mul_f32 v[56:57], v[128:129], v[144:145]
	v_pk_mul_f32 v[18:19], v[142:143], v[18:19]
	v_pk_mul_f32 v[16:17], v[140:141], v[16:17]
	v_pk_mul_f32 v[70:71], v[138:139], v[70:71]
	v_pk_mul_f32 v[68:69], v[136:137], v[68:69]
	v_pk_mul_f32 v[86:87], v[86:87], v[110:111]
	v_pk_mul_f32 v[84:85], v[84:85], v[108:109]
	v_pk_mul_f32 v[82:83], v[82:83], v[106:107]
	v_pk_mul_f32 v[80:81], v[80:81], v[104:105]
	v_add_u32_e32 v20, s92, v176
	v_ashrrev_i32_e32 v21, 31, v20
	v_lshlrev_b64 v[20:21], 12, v[20:21]
	v_lshl_add_u64 v[196:197], v[156:157], 0, v[20:21]
	ds_read_b128 v[20:23], v170
	ds_read_b128 v[24:27], v170 offset:64
	ds_read_b128 v[88:91], v170 offset:16896
	ds_read_b128 v[92:95], v170 offset:16960
	ds_read_b128 v[96:99], v170 offset:8448
	ds_read_b128 v[100:103], v170 offset:128
	ds_read_b128 v[104:107], v170 offset:8512
	ds_read_b128 v[108:111], v170 offset:8576
	ds_read_b128 v[112:115], v170 offset:25344
	ds_read_b128 v[116:119], v170 offset:17024
	ds_read_b128 v[120:123], v170 offset:25408
	ds_read_b128 v[124:127], v170 offset:25472
	v_cvt_pk_bf16_f32 v128, v84, v85
	v_cvt_pk_bf16_f32 v129, v86, v87
	v_cvt_pk_bf16_f32 v130, v80, v81
	v_cvt_pk_bf16_f32 v131, v82, v83
	s_waitcnt lgkmcnt(0)
; __device__ __forceinline__ void scan_compute(const char* cur, const bf16x8 (&vf)[2], f32x4 (&st)[16],
;                                              u16* O, const int fr, const int fq) {
;     ...
;   {
;     f32x4 oacc[4];
;     u32x4 qf[3][4];
;     bf16x8 af[2][4];
; #pragma unroll
;     for (int qt = 0; qt < 4; ++qt) oacc[qt] = f32x4{0.f, 0.f, 0.f, 0.f};
;     LOADQ(0, 0);
;     LOADQ(1, 1);
; #pragma unroll
;     for (int s = 0; s < 8; ++s) {
;       if (s < 6) { LOADQ((s + 2) % 3, s + 2); }
;       else if (s == 6) {
; #pragma unroll
;         for (int qt = 0; qt < 4; ++qt) af[0][qt] = *(const bf16x8*)(AMl0 + (16 * qt) * 64);
;       } else {
; #pragma unroll
;         for (int qt = 0; qt < 4; ++qt) af[1][qt] = *(const bf16x8*)(AMl1 + (16 * qt) * 64);
;       }
;       u32x4 sw;
;       sw[0] = pack2(st[2 * s][0], st[2 * s][1]);
;       sw[1] = pack2(st[2 * s][2], st[2 * s][3]);
;       sw[2] = pack2(st[2 * s + 1][0], st[2 * s + 1][1]);
;       sw[3] = pack2(st[2 * s + 1][2], st[2 * s + 1][3]);
;       bf16x8 sf = __builtin_bit_cast(bf16x8, sw);
;       __builtin_amdgcn_sched_barrier(0);
; #pragma unroll
;       for (int qt = 0; qt < 4; ++qt)
;         oacc[qt] = __builtin_amdgcn_mfma_f32_16x16x32_bf16(sf, __builtin_bit_cast(bf16x8, qf[s % 3][qt]), oacc[qt], 0, 0, 0);
;       __builtin_amdgcn_sched_barrier(0);
;     }
; #pragma unroll
;     for (int qt = 0; qt < 4; ++qt)
;       oacc[qt] = __builtin_amdgcn_mfma_f32_16x16x32_bf16(vf[0], af[0][qt], oacc[qt], 0, 0, 0);
;     __builtin_amdgcn_sched_barrier(0);
; #pragma unroll
;     for (int qt = 0; qt < 4; ++qt)
;       oacc[qt] = __builtin_amdgcn_mfma_f32_16x16x32_bf16(vf[1], af[1][qt], oacc[qt], 0, 0, 0);
;     __builtin_amdgcn_sched_barrier(0);
; #pragma unroll
;     for (int qt = 0; qt < 4; ++qt) {
;       u32x2 ov;
;       ov[0] = pack2(oacc[qt][0], oacc[qt][1]);
;       ov[1] = pack2(oacc[qt][2], oacc[qt][3]);
;       *(u32x2*)(O + (size_t)(16 * qt) * 2048) = ov;
;     }
;   }
;     ...
;   {
;     bf16x8 kf[3][2][2];
;     f32x4 eb[4][2];
;     ...
;     LOADK(0, 0, 0);
;     LOADK(1, 1, 1);
; #pragma unroll
;     for (int g = 0; g < 8; ++g) {
;       if (g < 6) { LOADK((g + 2) % 3, (g + 2) & 3, g + 2); }
	s_nop 0
	v_mfma_f32_16x16x32_bf16 v[20:23], v[128:131], v[20:23], 0
	v_mfma_f32_16x16x32_bf16 v[96:99], v[128:131], v[96:99], 0
	v_mfma_f32_16x16x32_bf16 v[88:91], v[128:131], v[88:91], 0
	v_mfma_f32_16x16x32_bf16 v[112:115], v[128:131], v[112:115], 0
	ds_read_b128 v[128:131], v170 offset:192
	ds_read_b128 v[132:135], v170 offset:8640
	ds_read_b128 v[136:139], v170 offset:17088
	ds_read_b128 v[140:143], v170 offset:25536
	v_cvt_pk_bf16_f32 v144, v72, v73
	v_cvt_pk_bf16_f32 v145, v74, v75
	v_cvt_pk_bf16_f32 v146, v76, v77
	v_cvt_pk_bf16_f32 v147, v78, v79
	s_nop 1
	v_mfma_f32_16x16x32_bf16 v[20:23], v[144:147], v[24:27], v[20:23]
	v_mfma_f32_16x16x32_bf16 v[24:27], v[144:147], v[104:107], v[96:99]
	v_mfma_f32_16x16x32_bf16 v[88:91], v[144:147], v[92:95], v[88:91]
	v_mfma_f32_16x16x32_bf16 v[92:95], v[144:147], v[120:123], v[112:115]
	s_nop 0
	ds_read_b128 v[96:99], v170 offset:256
	ds_read_b128 v[104:107], v170 offset:8704
	ds_read_b128 v[112:115], v170 offset:17152
	ds_read_b128 v[120:123], v170 offset:25600
	v_cvt_pk_bf16_f32 v144, v28, v29
	v_cvt_pk_bf16_f32 v145, v30, v31
	v_cvt_pk_bf16_f32 v146, v32, v33
	v_cvt_pk_bf16_f32 v147, v34, v35
	s_nop 1
	v_mfma_f32_16x16x32_bf16 v[20:23], v[144:147], v[100:103], v[20:23]
	v_mfma_f32_16x16x32_bf16 v[24:27], v[144:147], v[108:111], v[24:27]
	v_mfma_f32_16x16x32_bf16 v[88:91], v[144:147], v[116:119], v[88:91]
	v_mfma_f32_16x16x32_bf16 v[92:95], v[144:147], v[124:127], v[92:95]
	ds_read_b128 v[100:103], v170 offset:320
	ds_read_b128 v[108:111], v170 offset:8768
	ds_read_b128 v[116:119], v170 offset:17216
	ds_read_b128 v[124:127], v170 offset:25664
	v_cvt_pk_bf16_f32 v144, v36, v37
	v_cvt_pk_bf16_f32 v145, v38, v39
	v_cvt_pk_bf16_f32 v146, v40, v41
	v_cvt_pk_bf16_f32 v147, v42, v43
	s_waitcnt lgkmcnt(0)
	s_nop 0
	v_mfma_f32_16x16x32_bf16 v[20:23], v[144:147], v[128:131], v[20:23]
	v_mfma_f32_16x16x32_bf16 v[24:27], v[144:147], v[132:135], v[24:27]
	v_mfma_f32_16x16x32_bf16 v[88:91], v[144:147], v[136:139], v[88:91]
	v_mfma_f32_16x16x32_bf16 v[92:95], v[144:147], v[140:143], v[92:95]
	ds_read_b128 v[128:131], v170 offset:384
	ds_read_b128 v[132:135], v170 offset:8832
	ds_read_b128 v[136:139], v170 offset:17280
	ds_read_b128 v[140:143], v170 offset:25728
	v_cvt_pk_bf16_f32 v144, v44, v45
	v_cvt_pk_bf16_f32 v145, v46, v47
	v_cvt_pk_bf16_f32 v146, v48, v49
	v_cvt_pk_bf16_f32 v147, v50, v51
	s_nop 1
	v_mfma_f32_16x16x32_bf16 v[20:23], v[144:147], v[96:99], v[20:23]
	v_mfma_f32_16x16x32_bf16 v[24:27], v[144:147], v[104:107], v[24:27]
	v_mfma_f32_16x16x32_bf16 v[88:91], v[144:147], v[112:115], v[88:91]
	v_mfma_f32_16x16x32_bf16 v[92:95], v[144:147], v[120:123], v[92:95]
	ds_read_b128 v[96:99], v170 offset:448
	ds_read_b128 v[104:107], v170 offset:8896
	ds_read_b128 v[112:115], v170 offset:17344
	ds_read_b128 v[120:123], v170 offset:25792
	v_cvt_pk_bf16_f32 v144, v60, v61
	v_cvt_pk_bf16_f32 v145, v62, v63
	v_cvt_pk_bf16_f32 v146, v64, v65
	v_cvt_pk_bf16_f32 v147, v66, v67
	s_nop 1
	v_mfma_f32_16x16x32_bf16 v[20:23], v[144:147], v[100:103], v[20:23]
	v_mfma_f32_16x16x32_bf16 v[24:27], v[144:147], v[108:111], v[24:27]
	v_mfma_f32_16x16x32_bf16 v[88:91], v[144:147], v[116:119], v[88:91]
	v_mfma_f32_16x16x32_bf16 v[92:95], v[144:147], v[124:127], v[92:95]
	ds_read_b128 v[100:103], v173
	ds_read_b128 v[108:111], v173 offset:2048
	ds_read_b128 v[116:119], v173 offset:4096
	ds_read_b128 v[124:127], v173 offset:6144
	v_cvt_pk_bf16_f32 v144, v52, v53
	v_cvt_pk_bf16_f32 v145, v54, v55
	v_cvt_pk_bf16_f32 v146, v56, v57
	v_cvt_pk_bf16_f32 v147, v58, v59
	s_waitcnt lgkmcnt(0)
	s_nop 0
	v_mfma_f32_16x16x32_bf16 v[20:23], v[144:147], v[128:131], v[20:23]
	v_mfma_f32_16x16x32_bf16 v[24:27], v[144:147], v[132:135], v[24:27]
	v_mfma_f32_16x16x32_bf16 v[88:91], v[144:147], v[136:139], v[88:91]
	v_mfma_f32_16x16x32_bf16 v[92:95], v[144:147], v[140:143], v[92:95]
	ds_read_b128 v[128:131], v171 offset:6144
	ds_read_b128 v[132:135], v171 offset:4096
	ds_read_b128 v[136:139], v171 offset:2048
	ds_read_b128 v[140:143], v171
	v_cvt_pk_bf16_f32 v144, v16, v17
	v_cvt_pk_bf16_f32 v145, v18, v19
	v_cvt_pk_bf16_f32 v146, v68, v69
	v_cvt_pk_bf16_f32 v147, v70, v71
	s_nop 1
	v_mfma_f32_16x16x32_bf16 v[20:23], v[144:147], v[96:99], v[20:23]
	v_mfma_f32_16x16x32_bf16 v[24:27], v[144:147], v[104:107], v[24:27]
	v_mfma_f32_16x16x32_bf16 v[88:91], v[144:147], v[112:115], v[88:91]
	v_mfma_f32_16x16x32_bf16 v[92:95], v[144:147], v[120:123], v[92:95]
	v_mfma_f32_16x16x32_bf16 v[20:23], v[12:15], v[100:103], v[20:23]
	v_mfma_f32_16x16x32_bf16 v[24:27], v[12:15], v[108:111], v[24:27]
	v_mfma_f32_16x16x32_bf16 v[88:91], v[12:15], v[116:119], v[88:91]
	v_mfma_f32_16x16x32_bf16 v[92:95], v[12:15], v[124:127], v[92:95]
	s_waitcnt lgkmcnt(0)
	v_mfma_f32_16x16x32_bf16 v[20:23], v[8:11], v[140:143], v[20:23]
	v_mfma_f32_16x16x32_bf16 v[24:27], v[8:11], v[136:139], v[24:27]
	v_mfma_f32_16x16x32_bf16 v[88:91], v[8:11], v[132:135], v[88:91]
	v_mfma_f32_16x16x32_bf16 v[92:95], v[8:11], v[128:131], v[92:95]
	s_nop 4
	v_cvt_pk_bf16_f32 v20, v20, v21
	v_cvt_pk_bf16_f32 v21, v22, v23
	v_add_co_u32_e32 v22, vcc, s2, v196
	global_store_dwordx2 v[196:197], v[20:21], off
	v_cvt_pk_bf16_f32 v20, v24, v25
	v_cvt_pk_bf16_f32 v21, v26, v27
	v_addc_co_u32_e32 v23, vcc, 0, v197, vcc
	global_store_dwordx2 v[22:23], v[20:21], off
	v_add_co_u32_e32 v22, vcc, s11, v196
	v_cvt_pk_bf16_f32 v20, v88, v89
	v_cvt_pk_bf16_f32 v21, v90, v91
	v_addc_co_u32_e32 v23, vcc, 0, v197, vcc
	global_store_dwordx2 v[22:23], v[20:21], off
	v_cvt_pk_bf16_f32 v198, v92, v93
	v_cvt_pk_bf16_f32 v199, v94, v95
	ds_read_b128 v[20:23], v174
	ds_read_b128 v[24:27], v174 offset:2048
	ds_read_b128 v[88:91], v172
	ds_read_b128 v[92:95], v172 offset:2048
	ds_read_b128 v[96:99], v175
	ds_read_b128 v[100:103], v175 offset:64
	ds_read_b128 v[104:107], v174 offset:4096
	ds_read_b128 v[108:111], v174 offset:6144
	ds_read_b128 v[112:115], v172 offset:4096
	ds_read_b128 v[116:119], v172 offset:6144
	ds_read_b128 v[120:123], v175 offset:128
	ds_read_b128 v[124:127], v175 offset:192
	ds_read_b128 v[128:131], v174 offset:8192
	ds_read_b128 v[132:135], v174 offset:10240
	ds_read_b128 v[136:139], v172 offset:8192
	ds_read_b128 v[140:143], v172 offset:10240
	ds_read_b128 v[144:147], v175 offset:256
	ds_read_b128 v[148:151], v175 offset:320
	v_add_co_u32_e32 v196, vcc, s88, v196
	s_nop 1
	v_addc_co_u32_e32 v197, vcc, 0, v197, vcc
	global_store_dwordx2 v[196:197], v[198:199], off
	s_waitcnt lgkmcnt(0)
; __device__ __forceinline__ void scan_compute(const char* cur, const bf16x8 (&vf)[2], f32x4 (&st)[16],
;                                              u16* O, const int fr, const int fq) {
;     ...
; #pragma unroll
;     for (int g = 0; g < 8; ++g) {
;       if (g < 6) { LOADK((g + 2) % 3, (g + 2) & 3, g + 2); }
;       __builtin_amdgcn_sched_barrier(0);
; #pragma unroll
;       for (int u = 0; u < 2; ++u) {
;         st[2 * g + u] = __builtin_amdgcn_mfma_f32_16x16x32_bf16(kf[g % 3][u][0], vf[0], st[2 * g + u], 0, 0, 0);
;       }
; #pragma unroll
;       for (int u = 0; u < 2; ++u) {
;         st[2 * g + u] = __builtin_amdgcn_mfma_f32_16x16x32_bf16(kf[g % 3][u][1], vf[1], st[2 * g + u], 0, 0, 0);
;       }
;       if (g > 0) { st[2 * g - 2] *= eb[(g - 1) & 3][0]; st[2 * g - 1] *= eb[(g - 1) & 3][1]; }
;       __builtin_amdgcn_sched_barrier(0);
;     }
;     st[14] *= eb[7 & 3][0];
;     st[15] *= eb[7 & 3][1];
; __device__ void gla_scan_item(const Params& p, int id) {
;     ...
;     asm volatile("s_waitcnt vmcnt(0)" ::: "memory");
;     __syncthreads();
;     BLOB_DMA(nc2, 0);
;     VT_LOAD(vfA, nc2);
;     __builtin_amdgcn_sched_barrier(0);
;     scan_compute(smem + BLOB_BYTES, vfB, st, O + (size_t)(nc1 * 64 + fr) * 2048, fr, fq);
;     asm volatile("s_waitcnt vmcnt(0)" ::: "memory");
;     __syncthreads();
;   }
	v_mfma_f32_16x16x32_bf16 v[20:23], v[20:23], v[12:15], v[84:87]
	v_mfma_f32_16x16x32_bf16 v[24:27], v[24:27], v[12:15], v[80:83]
	v_mfma_f32_16x16x32_bf16 v[20:23], v[88:91], v[8:11], v[20:23]
	v_mfma_f32_16x16x32_bf16 v[24:27], v[92:95], v[8:11], v[24:27]
	s_nop 0
	ds_read_b128 v[80:83], v174 offset:12288
	ds_read_b128 v[84:87], v174 offset:14336
	ds_read_b128 v[88:91], v172 offset:12288
	ds_read_b128 v[92:95], v172 offset:14336
	ds_read_b128 v[196:199], v175 offset:384
	ds_read_b128 v[200:203], v175 offset:448
	v_mfma_f32_16x16x32_bf16 v[72:75], v[104:107], v[12:15], v[72:75]
	v_mul_f32_e64 v22, v98, v22
	v_mul_f32_e64 v23, v99, v23
	v_pk_mul_f32 v[20:21], v[96:97], v[20:21]
	v_pk_mul_f32 v[26:27], v[102:103], v[26:27]
	v_mfma_f32_16x16x32_bf16 v[76:79], v[108:111], v[12:15], v[76:79]
	v_mul_f32_e64 v24, v100, v24
	v_mul_f32_e64 v25, v101, v25
	v_mfma_f32_16x16x32_bf16 v[72:75], v[112:115], v[8:11], v[72:75]
	v_mfma_f32_16x16x32_bf16 v[76:79], v[116:119], v[8:11], v[76:79]
	ds_read_b128 v[96:99], v174 offset:16384
	ds_read_b128 v[100:103], v174 offset:18432
	ds_read_b128 v[104:107], v172 offset:16384
	ds_read_b128 v[108:111], v172 offset:18432
	ds_read_b128 v[112:115], v175 offset:512
	ds_read_b128 v[116:119], v175 offset:576
	v_mfma_f32_16x16x32_bf16 v[28:31], v[128:131], v[12:15], v[28:31]
	v_mfma_f32_16x16x32_bf16 v[128:131], v[132:135], v[12:15], v[32:35]
	v_mfma_f32_16x16x32_bf16 v[132:135], v[136:139], v[8:11], v[28:31]
	s_nop 1
	v_mul_f32_e64 v34, v126, v78
	v_mul_f32_e64 v35, v127, v79
	v_pk_mul_f32 v[32:33], v[124:125], v[76:77]
	s_nop 0
	v_pk_mul_f32 v[30:31], v[122:123], v[74:75]
	v_pk_mul_f32 v[28:29], v[120:121], v[72:73]
	v_mfma_f32_16x16x32_bf16 v[72:75], v[140:143], v[8:11], v[128:131]
	ds_read_b128 v[76:79], v174 offset:20480
	ds_read_b128 v[120:123], v174 offset:22528
	ds_read_b128 v[124:127], v172 offset:20480
	ds_read_b128 v[128:131], v172 offset:22528
	ds_read_b128 v[136:139], v175 offset:640
	ds_read_b128 v[140:143], v175 offset:704
	s_waitcnt lgkmcnt(0)
	v_mfma_f32_16x16x32_bf16 v[36:39], v[80:83], v[12:15], v[36:39]
	v_mfma_f32_16x16x32_bf16 v[80:83], v[84:87], v[12:15], v[40:43]
	s_nop 2
	v_mul_f32_e64 v42, v150, v74
	v_mul_f32_e64 v43, v151, v75
	v_pk_mul_f32 v[40:41], v[148:149], v[72:73]
	v_mfma_f32_16x16x32_bf16 v[72:75], v[92:95], v[8:11], v[80:83]
	v_mfma_f32_16x16x32_bf16 v[84:87], v[88:91], v[8:11], v[36:39]
	s_nop 2
	v_mul_f32_e64 v38, v146, v134
	v_mul_f32_e64 v39, v147, v135
	v_pk_mul_f32 v[36:37], v[144:145], v[132:133]
	ds_read_b128 v[80:83], v174 offset:24576
	ds_read_b128 v[88:91], v174 offset:26624
	ds_read_b128 v[92:95], v172 offset:24576
	ds_read_b128 v[132:135], v172 offset:26624
	ds_read_b128 v[144:147], v175 offset:768
	ds_read_b128 v[148:151], v175 offset:832
	v_mfma_f32_16x16x32_bf16 v[44:47], v[96:99], v[12:15], v[44:47]
	v_mfma_f32_16x16x32_bf16 v[96:99], v[100:103], v[12:15], v[48:51]
	s_nop 2
	v_mul_f32_e64 v50, v202, v74
	v_mul_f32_e64 v51, v203, v75
	v_pk_mul_f32 v[48:49], v[200:201], v[72:73]
	v_mfma_f32_16x16x32_bf16 v[72:75], v[108:111], v[8:11], v[96:99]
	v_mfma_f32_16x16x32_bf16 v[100:103], v[104:107], v[8:11], v[44:47]
	s_nop 2
	v_mul_f32_e64 v46, v198, v86
	v_mul_f32_e64 v47, v199, v87
	v_pk_mul_f32 v[44:45], v[196:197], v[84:85]
	ds_read_b128 v[84:87], v174 offset:28672
	ds_read_b128 v[96:99], v174 offset:30720
	ds_read_b128 v[104:107], v172 offset:28672
	ds_read_b128 v[108:111], v172 offset:30720
	ds_read_b128 v[196:199], v175 offset:896
	ds_read_b128 v[200:203], v175 offset:960
	v_mfma_f32_16x16x32_bf16 v[60:63], v[76:79], v[12:15], v[60:63]
	v_mfma_f32_16x16x32_bf16 v[76:79], v[120:123], v[12:15], v[64:67]
	s_nop 2
	v_mul_f32_e64 v66, v118, v74
	v_mul_f32_e64 v67, v119, v75
	v_pk_mul_f32 v[64:65], v[116:117], v[72:73]
	v_mfma_f32_16x16x32_bf16 v[72:75], v[128:131], v[8:11], v[76:79]
	v_mfma_f32_16x16x32_bf16 v[120:123], v[124:127], v[8:11], v[60:63]
	s_nop 2
	v_mul_f32_e64 v62, v114, v102
	v_mul_f32_e64 v63, v115, v103
	v_pk_mul_f32 v[60:61], v[112:113], v[100:101]
	s_waitcnt lgkmcnt(0)
	v_mfma_f32_16x16x32_bf16 v[76:79], v[88:91], v[12:15], v[56:59]
	v_mfma_f32_16x16x32_bf16 v[52:55], v[80:83], v[12:15], v[52:55]
	s_nop 1
	v_mul_f32_e64 v58, v142, v74
	v_mul_f32_e64 v59, v143, v75
	v_pk_mul_f32 v[56:57], v[140:141], v[72:73]
	v_mfma_f32_16x16x32_bf16 v[76:79], v[132:135], v[8:11], v[76:79]
	v_mfma_f32_16x16x32_bf16 v[80:83], v[92:95], v[8:11], v[52:55]
	s_nop 2
	v_mul_f32_e64 v54, v138, v122
	v_mul_f32_e64 v55, v139, v123
	v_pk_mul_f32 v[52:53], v[136:137], v[120:121]
	v_mfma_f32_16x16x32_bf16 v[16:19], v[84:87], v[12:15], v[16:19]
	s_nop 0
	v_mul_f32_e64 v74, v146, v82
	v_mul_f32_e64 v75, v147, v83
	v_pk_mul_f32 v[72:73], v[144:145], v[80:81]
	v_pk_mul_f32 v[78:79], v[150:151], v[78:79]
	v_mfma_f32_16x16x32_bf16 v[12:15], v[96:99], v[12:15], v[68:71]
	v_mul_f32_e64 v76, v148, v76
	v_mul_f32_e64 v77, v149, v77
	v_mfma_f32_16x16x32_bf16 v[16:19], v[104:107], v[8:11], v[16:19]
	v_mfma_f32_16x16x32_bf16 v[8:11], v[108:111], v[8:11], v[12:15]
.Lsc_skipB:
	s_waitcnt vmcnt(0)
	s_nop 6
	v_mul_f32_e64 v70, v198, v18
	v_mul_f32_e64 v71, v199, v19
	v_pk_mul_f32 v[68:69], v[196:197], v[16:17]
	v_pk_mul_f32 v[18:19], v[202:203], v[10:11]
	v_pk_mul_f32 v[16:17], v[200:201], v[8:9]
	s_add_i32 s94, s94, 2
	s_add_i32 s92, s92, s93
	s_andn2_b64 vcc, exec, s[84:85]
	s_add_i32 s72, s72, s6
	s_waitcnt vmcnt(0)
	s_barrier
	s_cbranch_vccz .LBB0_423

; __device__ __forceinline__ void scan_compute(const char* cur, const bf16x8 (&vf)[2], f32x4 (&st)[16],
;                                              u16* O, const int fr, const int fq) {
;   const u16* QEl = (const u16*)(cur + B_QE) + fr * 264 + 8 * fq;
;   const u16* KETl0 = (const u16*)(cur + B_KET) + fr * 64 + ((fq ^ (fr & 7)) << 3);
;   const u16* KETl1 = (const u16*)(cur + B_KET) + fr * 64 + (((4 + fq) ^ (fr & 7)) << 3);
;   const u16* AMl0 = (const u16*)(cur + B_AM) + fr * 64 + ((fq ^ (fr & 7)) << 3);
;   const u16* AMl1 = (const u16*)(cur + B_AM) + fr * 64 + (((4 + fq) ^ (fr & 7)) << 3);
;   const float* EBLl = (const float*)(cur + B_EBL) + 4 * fq;
;     ...
;   {
;     f32x4 oacc[4];
;     u32x4 qf[3][4];
;     bf16x8 af[2][4];
; #pragma unroll
;     for (int qt = 0; qt < 4; ++qt) oacc[qt] = f32x4{0.f, 0.f, 0.f, 0.f};
;     LOADQ(0, 0);
;     LOADQ(1, 1);
; #pragma unroll
;     for (int s = 0; s < 8; ++s) {
;       if (s < 6) { LOADQ((s + 2) % 3, s + 2); }
;       else if (s == 6) {
; #pragma unroll
;         for (int qt = 0; qt < 4; ++qt) af[0][qt] = *(const bf16x8*)(AMl0 + (16 * qt) * 64);
;       } else {
; #pragma unroll
;         for (int qt = 0; qt < 4; ++qt) af[1][qt] = *(const bf16x8*)(AMl1 + (16 * qt) * 64);
;       }
;       u32x4 sw;
;       sw[0] = pack2(st[2 * s][0], st[2 * s][1]);
;       sw[1] = pack2(st[2 * s][2], st[2 * s][3]);
;       sw[2] = pack2(st[2 * s + 1][0], st[2 * s + 1][1]);
;       sw[3] = pack2(st[2 * s + 1][2], st[2 * s + 1][3]);
;       bf16x8 sf = __builtin_bit_cast(bf16x8, sw);
;       __builtin_amdgcn_sched_barrier(0);
; #pragma unroll
;       for (int qt = 0; qt < 4; ++qt)
;         oacc[qt] = __builtin_amdgcn_mfma_f32_16x16x32_bf16(sf, __builtin_bit_cast(bf16x8, qf[s % 3][qt]), oacc[qt], 0, 0, 0);
;       __builtin_amdgcn_sched_barrier(0);
;     }
; #pragma unroll
;     for (int qt = 0; qt < 4; ++qt)
;       oacc[qt] = __builtin_amdgcn_mfma_f32_16x16x32_bf16(vf[0], af[0][qt], oacc[qt], 0, 0, 0);
; __device__ void gla_scan_item(const Params& p, int id) {
;     ...
;   for (int n = 0; n < nch; n += 2) {
;     const int nc0 = cfirst + cstep * n, nc1 = nc0 + cstep;
;     const int nc2 = (n + 2 < nch) ? nc1 + cstep : nc1;
;     BLOB_DMA(nc1, BLOB_BYTES);
;     VT_LOAD(vfB, nc1);
;     __builtin_amdgcn_sched_barrier(0);
;     scan_compute(smem, vfA, st, O + (size_t)(nc0 * 64 + fr) * 2048, fr, fq);
.LBB0_430:
	s_ashr_i32 s73, s72, 31
	s_cmp_ge_u32 s94, s90
	s_cselect_b64 s[84:85], -1, 0
	s_cmp_lt_u32 s94, s90
	s_cselect_b32 s86, s91, 0
	s_lshl_b64 s[8:9], s[72:73], 18
	v_lshl_add_u64 v[8:9], v[158:159], 0, s[8:9]
	global_load_dwordx4 v[12:15], v[8:9], off
	s_nop 0
	global_load_dwordx4 v[8:11], v[8:9], off offset:64
	s_add_i32 s86, s86, s72
	s_cmp_lg_u32 s99, 0
	s_cbranch_scc1 .Lsc_skipA
	v_add_u32_e32 v80, s92, v163
	v_ashrrev_i32_e32 v81, 31, v80
	v_lshlrev_b64 v[80:81], 12, v[80:81]
	v_lshl_add_u64 v[196:197], v[156:157], 0, v[80:81]
	ds_read_b128 v[80:83], v164
	ds_read_b128 v[84:87], v164 offset:64
	ds_read_b128 v[88:91], v164 offset:16896
	ds_read_b128 v[92:95], v164 offset:16960
	ds_read_b128 v[96:99], v164 offset:8448
	ds_read_b128 v[100:103], v164 offset:128
	ds_read_b128 v[104:107], v164 offset:8512
	ds_read_b128 v[108:111], v164 offset:8576
	ds_read_b128 v[112:115], v164 offset:25344
	ds_read_b128 v[116:119], v164 offset:17024
	ds_read_b128 v[120:123], v164 offset:25408
	ds_read_b128 v[124:127], v164 offset:25472
	v_cvt_pk_bf16_f32 v128, v20, v21
	v_cvt_pk_bf16_f32 v129, v22, v23
	v_cvt_pk_bf16_f32 v130, v24, v25
	v_cvt_pk_bf16_f32 v131, v26, v27
	s_waitcnt lgkmcnt(0)
	s_nop 0
	v_mfma_f32_16x16x32_bf16 v[80:83], v[128:131], v[80:83], 0
	v_mfma_f32_16x16x32_bf16 v[96:99], v[128:131], v[96:99], 0
	v_mfma_f32_16x16x32_bf16 v[88:91], v[128:131], v[88:91], 0
	v_mfma_f32_16x16x32_bf16 v[112:115], v[128:131], v[112:115], 0
	ds_read_b128 v[128:131], v164 offset:192
	ds_read_b128 v[132:135], v164 offset:8640
	ds_read_b128 v[136:139], v164 offset:17088
	ds_read_b128 v[140:143], v164 offset:25536
	v_cvt_pk_bf16_f32 v144, v28, v29
	v_cvt_pk_bf16_f32 v145, v30, v31
	v_cvt_pk_bf16_f32 v146, v32, v33
	v_cvt_pk_bf16_f32 v147, v34, v35
	s_nop 1
	v_mfma_f32_16x16x32_bf16 v[80:83], v[144:147], v[84:87], v[80:83]
	v_mfma_f32_16x16x32_bf16 v[84:87], v[144:147], v[104:107], v[96:99]
	v_mfma_f32_16x16x32_bf16 v[88:91], v[144:147], v[92:95], v[88:91]
	v_mfma_f32_16x16x32_bf16 v[92:95], v[144:147], v[120:123], v[112:115]
	s_nop 0
	ds_read_b128 v[96:99], v164 offset:256
	ds_read_b128 v[104:107], v164 offset:8704
	ds_read_b128 v[112:115], v164 offset:17152
	ds_read_b128 v[120:123], v164 offset:25600
	v_cvt_pk_bf16_f32 v144, v36, v37
	v_cvt_pk_bf16_f32 v145, v38, v39
	v_cvt_pk_bf16_f32 v146, v40, v41
	v_cvt_pk_bf16_f32 v147, v42, v43
	s_nop 1
	v_mfma_f32_16x16x32_bf16 v[80:83], v[144:147], v[100:103], v[80:83]
	v_mfma_f32_16x16x32_bf16 v[84:87], v[144:147], v[108:111], v[84:87]
	v_mfma_f32_16x16x32_bf16 v[88:91], v[144:147], v[116:119], v[88:91]
	v_mfma_f32_16x16x32_bf16 v[92:95], v[144:147], v[124:127], v[92:95]
	ds_read_b128 v[100:103], v164 offset:320
	ds_read_b128 v[108:111], v164 offset:8768
	ds_read_b128 v[116:119], v164 offset:17216
	ds_read_b128 v[124:127], v164 offset:25664
	v_cvt_pk_bf16_f32 v144, v44, v45
	v_cvt_pk_bf16_f32 v145, v46, v47
	v_cvt_pk_bf16_f32 v146, v48, v49
	v_cvt_pk_bf16_f32 v147, v50, v51
	s_waitcnt lgkmcnt(0)
	s_nop 0
	v_mfma_f32_16x16x32_bf16 v[80:83], v[144:147], v[128:131], v[80:83]
	v_mfma_f32_16x16x32_bf16 v[84:87], v[144:147], v[132:135], v[84:87]
	v_mfma_f32_16x16x32_bf16 v[88:91], v[144:147], v[136:139], v[88:91]
	v_mfma_f32_16x16x32_bf16 v[92:95], v[144:147], v[140:143], v[92:95]
	ds_read_b128 v[128:131], v164 offset:384
	ds_read_b128 v[132:135], v164 offset:8832
	ds_read_b128 v[136:139], v164 offset:17280
	ds_read_b128 v[140:143], v164 offset:25728
	v_cvt_pk_bf16_f32 v144, v60, v61
	v_cvt_pk_bf16_f32 v145, v62, v63
	v_cvt_pk_bf16_f32 v146, v64, v65
	v_cvt_pk_bf16_f32 v147, v66, v67
	s_nop 1
	v_mfma_f32_16x16x32_bf16 v[80:83], v[144:147], v[96:99], v[80:83]
	v_mfma_f32_16x16x32_bf16 v[84:87], v[144:147], v[104:107], v[84:87]
	v_mfma_f32_16x16x32_bf16 v[88:91], v[144:147], v[112:115], v[88:91]
	v_mfma_f32_16x16x32_bf16 v[92:95], v[144:147], v[120:123], v[92:95]
	ds_read_b128 v[96:99], v164 offset:448
	ds_read_b128 v[104:107], v164 offset:8896
	ds_read_b128 v[112:115], v164 offset:17344
	ds_read_b128 v[120:123], v164 offset:25792
	v_cvt_pk_bf16_f32 v144, v52, v53
	v_cvt_pk_bf16_f32 v145, v54, v55
	v_cvt_pk_bf16_f32 v146, v56, v57
	v_cvt_pk_bf16_f32 v147, v58, v59
	s_nop 1
	v_mfma_f32_16x16x32_bf16 v[80:83], v[144:147], v[100:103], v[80:83]
	v_mfma_f32_16x16x32_bf16 v[84:87], v[144:147], v[108:111], v[84:87]
	v_mfma_f32_16x16x32_bf16 v[88:91], v[144:147], v[116:119], v[88:91]
	v_mfma_f32_16x16x32_bf16 v[92:95], v[144:147], v[124:127], v[92:95]
	ds_read_b128 v[100:103], v167
	ds_read_b128 v[108:111], v167 offset:2048
	ds_read_b128 v[116:119], v167 offset:4096
	ds_read_b128 v[124:127], v167 offset:6144
	v_cvt_pk_bf16_f32 v144, v72, v73
	v_cvt_pk_bf16_f32 v145, v74, v75
	v_cvt_pk_bf16_f32 v146, v76, v77
	v_cvt_pk_bf16_f32 v147, v78, v79
	s_waitcnt lgkmcnt(0)
	s_nop 0
	v_mfma_f32_16x16x32_bf16 v[80:83], v[144:147], v[128:131], v[80:83]
	v_mfma_f32_16x16x32_bf16 v[84:87], v[144:147], v[132:135], v[84:87]
	v_mfma_f32_16x16x32_bf16 v[88:91], v[144:147], v[136:139], v[88:91]
	v_mfma_f32_16x16x32_bf16 v[92:95], v[144:147], v[140:143], v[92:95]
	ds_read_b128 v[128:131], v165 offset:6144
	ds_read_b128 v[132:135], v165 offset:4096
	ds_read_b128 v[136:139], v165 offset:2048
	ds_read_b128 v[140:143], v165
	v_cvt_pk_bf16_f32 v144, v68, v69
	v_cvt_pk_bf16_f32 v145, v70, v71
	v_cvt_pk_bf16_f32 v146, v16, v17
	v_cvt_pk_bf16_f32 v147, v18, v19
	s_nop 1
	v_mfma_f32_16x16x32_bf16 v[80:83], v[144:147], v[96:99], v[80:83]
	v_mfma_f32_16x16x32_bf16 v[84:87], v[144:147], v[104:107], v[84:87]
	v_mfma_f32_16x16x32_bf16 v[88:91], v[144:147], v[112:115], v[88:91]
	v_mfma_f32_16x16x32_bf16 v[92:95], v[144:147], v[120:123], v[92:95]
	v_mfma_f32_16x16x32_bf16 v[80:83], v[4:7], v[100:103], v[80:83]
	v_mfma_f32_16x16x32_bf16 v[84:87], v[4:7], v[108:111], v[84:87]
	v_mfma_f32_16x16x32_bf16 v[88:91], v[4:7], v[116:119], v[88:91]
	v_mfma_f32_16x16x32_bf16 v[92:95], v[4:7], v[124:127], v[92:95]
	s_waitcnt lgkmcnt(0)
; __device__ __forceinline__ void scan_compute(const char* cur, const bf16x8 (&vf)[2], f32x4 (&st)[16],
;                                              u16* O, const int fr, const int fq) {
;     ...
; #pragma unroll
;     for (int qt = 0; qt < 4; ++qt)
;       oacc[qt] = __builtin_amdgcn_mfma_f32_16x16x32_bf16(vf[0], af[0][qt], oacc[qt], 0, 0, 0);
;     __builtin_amdgcn_sched_barrier(0);
; #pragma unroll
;     for (int qt = 0; qt < 4; ++qt)
;       oacc[qt] = __builtin_amdgcn_mfma_f32_16x16x32_bf16(vf[1], af[1][qt], oacc[qt], 0, 0, 0);
;     __builtin_amdgcn_sched_barrier(0);
; #pragma unroll
;     for (int qt = 0; qt < 4; ++qt) {
;       u32x2 ov;
;       ov[0] = pack2(oacc[qt][0], oacc[qt][1]);
;       ov[1] = pack2(oacc[qt][2], oacc[qt][3]);
;       *(u32x2*)(O + (size_t)(16 * qt) * 2048) = ov;
;     }
;   }
;     ...
;   {
;     bf16x8 kf[3][2][2];
;     f32x4 eb[4][2];
;     ...
;     LOADK(0, 0, 0);
;     LOADK(1, 1, 1);
; #pragma unroll
;     for (int g = 0; g < 8; ++g) {
;       if (g < 6) { LOADK((g + 2) % 3, (g + 2) & 3, g + 2); }
;       __builtin_amdgcn_sched_barrier(0);
; #pragma unroll
;       for (int u = 0; u < 2; ++u) {
;         st[2 * g + u] = __builtin_amdgcn_mfma_f32_16x16x32_bf16(kf[g % 3][u][0], vf[0], st[2 * g + u], 0, 0, 0);
;       }
; #pragma unroll
;       for (int u = 0; u < 2; ++u) {
;         st[2 * g + u] = __builtin_amdgcn_mfma_f32_16x16x32_bf16(kf[g % 3][u][1], vf[1], st[2 * g + u], 0, 0, 0);
;       }
;       if (g > 0) { st[2 * g - 2] *= eb[(g - 1) & 3][0]; st[2 * g - 1] *= eb[(g - 1) & 3][1]; }
;       __builtin_amdgcn_sched_barrier(0);
;     }
;     st[14] *= eb[7 & 3][0];
;     st[15] *= eb[7 & 3][1];
; __device__ void gla_scan_item(const Params& p, int id) {
;     ...
;     asm volatile("s_waitcnt vmcnt(0)" ::: "memory");
;     __syncthreads();
;     BLOB_DMA(nc2, 0);
;     VT_LOAD(vfA, nc2);
;     __builtin_amdgcn_sched_barrier(0);
	v_mfma_f32_16x16x32_bf16 v[80:83], v[0:3], v[140:143], v[80:83]
	v_mfma_f32_16x16x32_bf16 v[84:87], v[0:3], v[136:139], v[84:87]
	v_mfma_f32_16x16x32_bf16 v[88:91], v[0:3], v[132:135], v[88:91]
	v_mfma_f32_16x16x32_bf16 v[92:95], v[0:3], v[128:131], v[92:95]
	s_nop 4
	v_cvt_pk_bf16_f32 v80, v80, v81
	v_cvt_pk_bf16_f32 v81, v82, v83
	v_add_co_u32_e32 v82, vcc, s2, v196
	global_store_dwordx2 v[196:197], v[80:81], off
	v_cvt_pk_bf16_f32 v80, v84, v85
	v_cvt_pk_bf16_f32 v81, v86, v87
	v_addc_co_u32_e32 v83, vcc, 0, v197, vcc
	global_store_dwordx2 v[82:83], v[80:81], off
	v_add_co_u32_e32 v82, vcc, s11, v196
	v_cvt_pk_bf16_f32 v80, v88, v89
	v_cvt_pk_bf16_f32 v81, v90, v91
	v_addc_co_u32_e32 v83, vcc, 0, v197, vcc
	global_store_dwordx2 v[82:83], v[80:81], off
	v_cvt_pk_bf16_f32 v198, v92, v93
	v_cvt_pk_bf16_f32 v199, v94, v95
	ds_read_b128 v[104:107], v168 offset:33792
	ds_read_b128 v[108:111], v168 offset:35840
	ds_read_b128 v[112:115], v166 offset:33792
	ds_read_b128 v[116:119], v166 offset:35840
	ds_read_b128 v[84:87], v169
	ds_read_b128 v[80:83], v169 offset:64
	ds_read_b128 v[120:123], v168 offset:37888
	ds_read_b128 v[124:127], v168 offset:39936
	ds_read_b128 v[128:131], v166 offset:37888
	ds_read_b128 v[132:135], v166 offset:39936
	ds_read_b128 v[92:95], v169 offset:128
	ds_read_b128 v[88:91], v169 offset:192
	ds_read_b128 v[136:139], v168 offset:41984
	ds_read_b128 v[140:143], v168 offset:44032
	ds_read_b128 v[144:147], v166 offset:41984
	ds_read_b128 v[148:151], v166 offset:44032
	ds_read_b128 v[100:103], v169 offset:256
	ds_read_b128 v[96:99], v169 offset:320
	v_add_co_u32_e32 v196, vcc, s88, v196
	s_nop 1
	v_addc_co_u32_e32 v197, vcc, 0, v197, vcc
	global_store_dwordx2 v[196:197], v[198:199], off
	s_waitcnt lgkmcnt(0)
	v_mfma_f32_16x16x32_bf16 v[20:23], v[104:107], v[4:7], v[20:23]
	v_mfma_f32_16x16x32_bf16 v[24:27], v[108:111], v[4:7], v[24:27]
	v_mfma_f32_16x16x32_bf16 v[108:111], v[112:115], v[0:3], v[20:23]
	v_mfma_f32_16x16x32_bf16 v[104:107], v[116:119], v[0:3], v[24:27]
	ds_read_b128 v[196:199], v168 offset:46080
	ds_read_b128 v[200:203], v168 offset:48128
	ds_read_b128 v[204:207], v166 offset:46080
	ds_read_b128 v[208:211], v166 offset:48128
	s_nop 1
	ds_read_b128 v[24:27], v169 offset:384
	ds_read_b128 v[20:23], v169 offset:448
	v_mfma_f32_16x16x32_bf16 v[28:31], v[120:123], v[4:7], v[28:31]
	v_mfma_f32_16x16x32_bf16 v[112:115], v[124:127], v[4:7], v[32:35]
	v_mfma_f32_16x16x32_bf16 v[32:35], v[128:131], v[0:3], v[28:31]
	v_mfma_f32_16x16x32_bf16 v[28:31], v[132:135], v[0:3], v[112:115]
	ds_read_b128 v[212:215], v168 offset:50176
	ds_read_b128 v[216:219], v168 offset:52224
	ds_read_b128 v[220:223], v166 offset:50176
	ds_read_b128 v[224:227], v166 offset:52224
	ds_read_b128 v[116:119], v169 offset:512
	s_nop 0
	ds_read_b128 v[112:115], v169 offset:576
	v_mfma_f32_16x16x32_bf16 v[36:39], v[136:139], v[4:7], v[36:39]
	v_mfma_f32_16x16x32_bf16 v[120:123], v[140:143], v[4:7], v[40:43]
	v_mfma_f32_16x16x32_bf16 v[40:43], v[144:147], v[0:3], v[36:39]
	v_mfma_f32_16x16x32_bf16 v[36:39], v[148:151], v[0:3], v[120:123]
	ds_read_b128 v[144:147], v168 offset:54272
	ds_read_b128 v[148:151], v168 offset:56320
	ds_read_b128 v[228:231], v166 offset:54272
	ds_read_b128 v[232:235], v166 offset:56320
	ds_read_b128 v[124:127], v169 offset:640
	s_nop 0
	ds_read_b128 v[120:123], v169 offset:704
	s_waitcnt lgkmcnt(0)
	v_mfma_f32_16x16x32_bf16 v[44:47], v[196:199], v[4:7], v[44:47]
	v_mfma_f32_16x16x32_bf16 v[128:131], v[200:203], v[4:7], v[48:51]
	v_mfma_f32_16x16x32_bf16 v[48:51], v[204:207], v[0:3], v[44:47]
	v_mfma_f32_16x16x32_bf16 v[44:47], v[208:211], v[0:3], v[128:131]
	ds_read_b128 v[196:199], v168 offset:58368
	ds_read_b128 v[200:203], v168 offset:60416
	ds_read_b128 v[204:207], v166 offset:58368
	ds_read_b128 v[208:211], v166 offset:60416
	ds_read_b128 v[132:135], v169 offset:768
	s_nop 0
	ds_read_b128 v[128:131], v169 offset:832
	v_mfma_f32_16x16x32_bf16 v[60:63], v[212:215], v[4:7], v[60:63]
	v_mfma_f32_16x16x32_bf16 v[136:139], v[216:219], v[4:7], v[64:67]
	v_mfma_f32_16x16x32_bf16 v[64:67], v[220:223], v[0:3], v[60:63]
	v_mfma_f32_16x16x32_bf16 v[60:63], v[224:227], v[0:3], v[136:139]
	ds_read_b128 v[212:215], v168 offset:62464
	ds_read_b128 v[216:219], v168 offset:64512
	ds_read_b128 v[220:223], v166 offset:62464
	ds_read_b128 v[224:227], v166 offset:64512
	ds_read_b128 v[140:143], v169 offset:896
	s_nop 0
	ds_read_b128 v[136:139], v169 offset:960
	v_mfma_f32_16x16x32_bf16 v[52:55], v[144:147], v[4:7], v[52:55]
	v_mfma_f32_16x16x32_bf16 v[144:147], v[148:151], v[4:7], v[56:59]
	v_mfma_f32_16x16x32_bf16 v[56:59], v[228:231], v[0:3], v[52:55]
	v_mfma_f32_16x16x32_bf16 v[52:55], v[232:235], v[0:3], v[144:147]
	s_waitcnt lgkmcnt(0)
	v_mfma_f32_16x16x32_bf16 v[72:75], v[196:199], v[4:7], v[72:75]
	v_mfma_f32_16x16x32_bf16 v[76:79], v[200:203], v[4:7], v[76:79]
	v_mfma_f32_16x16x32_bf16 v[148:151], v[204:207], v[0:3], v[72:75]
	v_mfma_f32_16x16x32_bf16 v[144:147], v[208:211], v[0:3], v[76:79]
	v_mfma_f32_16x16x32_bf16 v[68:71], v[212:215], v[4:7], v[68:71]
	v_mfma_f32_16x16x32_bf16 v[4:7], v[216:219], v[4:7], v[16:19]
	v_mfma_f32_16x16x32_bf16 v[16:19], v[220:223], v[0:3], v[68:71]
	v_mfma_f32_16x16x32_bf16 v[68:71], v[224:227], v[0:3], v[4:7]
.Lsc_skipA:
	v_mad_i64_i32 v[0:1], s[8:9], s86, v161, v[154:155]
	v_readfirstlane_b32 s8, v186
	v_lshl_add_u64 v[2:3], v[0:1], 0, s[28:29]
	s_mov_b32 m0, s8
	v_readfirstlane_b32 s8, v187
	s_waitcnt vmcnt(0)
	s_waitcnt vmcnt(0)
	s_barrier
	global_load_lds_dwordx4 v[2:3], off
	v_lshl_add_u64 v[2:3], v[0:1], 0, s[30:31]
	s_mov_b32 m0, s8
	v_readfirstlane_b32 s8, v188
	global_load_lds_dwordx4 v[2:3], off
	v_lshl_add_u64 v[2:3], v[0:1], 0, s[34:35]
	s_mov_b32 m0, s8
	v_readfirstlane_b32 s8, v189
	global_load_lds_dwordx4 v[2:3], off
	v_lshl_add_u64 v[2:3], v[0:1], 0, s[46:47]
	s_mov_b32 m0, s8
	v_readfirstlane_b32 s8, v190
	global_load_lds_dwordx4 v[2:3], off
	v_lshl_add_u64 v[2:3], v[0:1], 0, s[56:57]
	s_mov_b32 m0, s8
	v_readfirstlane_b32 s8, v191
	global_load_lds_dwordx4 v[2:3], off
	v_lshl_add_u64 v[2:3], v[0:1], 0, s[58:59]
	s_mov_b32 m0, s8
	v_readfirstlane_b32 s8, v192
	global_load_lds_dwordx4 v[2:3], off
	v_lshl_add_u64 v[2:3], v[0:1], 0, s[60:61]
	s_mov_b32 m0, s8
	v_readfirstlane_b32 s8, v193
	global_load_lds_dwordx4 v[2:3], off
	v_lshl_add_u64 v[2:3], v[0:1], 0, s[62:63]
	s_mov_b32 m0, s8
	v_readfirstlane_b32 s8, v152
	global_load_lds_dwordx4 v[2:3], off
	v_lshl_add_u64 v[2:3], v[0:1], 0, s[64:65]
	s_mov_b32 m0, s8
	s_and_b64 vcc, exec, s[0:1]
	global_load_lds_dwordx4 v[2:3], off
	s_cbranch_vccnz .LBB0_427
	v_readfirstlane_b32 s8, v162
	v_lshl_add_u64 v[0:1], v[0:1], 0, s[66:67]
	s_mov_b32 m0, s8
	s_nop 0
	global_load_lds_dwordx4 v[0:1], off
	s_branch .LBB0_427

; __global__ void __launch_bounds__(NTHREADS) fwd_megakernel(Params p) {
;   cg::grid_group grid = cg::this_grid();
;     ...
;   phase0(p);
;   grid.sync();
;   phase1(p);
;   xcd_barrier(xb);
;   phase2pre(p);
;   xcd_barrier(xb);
;   phase2(p, 0);
;   xcd_barrier(xb);
;   phase2c(p);
;   xcd_barrier(xb);
;   phase3(p);
;   xcd_barrier(xb);
;   phase4(p);
;   if (gridDim.x != 256) {
;     xcd_barrier(xb);
;     phase5(p);
;   }
; }
	.amdhsa_kernel _Z14fwd_megakernel6Params
		.amdhsa_group_segment_fixed_size 163840
		.amdhsa_private_segment_fixed_size 0
		.amdhsa_kernarg_size 536
		.amdhsa_user_sgpr_count 2
		.amdhsa_user_sgpr_dispatch_ptr 0
		.amdhsa_user_sgpr_queue_ptr 0
		.amdhsa_user_sgpr_kernarg_segment_ptr 1
		.amdhsa_user_sgpr_dispatch_id 0
		.amdhsa_user_sgpr_kernarg_preload_length 0
		.amdhsa_user_sgpr_kernarg_preload_offset 0
		.amdhsa_user_sgpr_private_segment_size 0
		.amdhsa_uses_dynamic_stack 0
		.amdhsa_enable_private_segment 0
		.amdhsa_system_sgpr_workgroup_id_x 1
		.amdhsa_system_sgpr_workgroup_id_y 0
		.amdhsa_system_sgpr_workgroup_id_z 0
		.amdhsa_system_sgpr_workgroup_info 0
		.amdhsa_system_vgpr_workitem_id 2
		.amdhsa_next_free_vgpr 256
		.amdhsa_next_free_sgpr 100
		.amdhsa_accum_offset 256
		.amdhsa_reserve_vcc 1
		.amdhsa_float_round_mode_32 0
		.amdhsa_float_round_mode_16_64 0
		.amdhsa_float_denorm_mode_32 3
		.amdhsa_float_denorm_mode_16_64 3
		.amdhsa_dx10_clamp 1
		.amdhsa_ieee_mode 1
		.amdhsa_fp16_overflow 0
		.amdhsa_tg_split 0
		.amdhsa_exception_fp_ieee_invalid_op 0
		.amdhsa_exception_fp_denorm_src 0
		.amdhsa_exception_fp_ieee_div_zero 0
		.amdhsa_exception_fp_ieee_overflow 0
		.amdhsa_exception_fp_ieee_underflow 0
		.amdhsa_exception_fp_ieee_inexact 0
		.amdhsa_exception_int_div_zero 0
	.end_amdhsa_kernel

; __global__ void __launch_bounds__(NTHREADS) fwd_megakernel(Params p) {
;   cg::grid_group grid = cg::this_grid();
;     ...
;   phase0(p);
;   grid.sync();
;   phase1(p);
;   xcd_barrier(xb);
;   phase2pre(p);
;   xcd_barrier(xb);
;   phase2(p, 0);
;   xcd_barrier(xb);
;   phase2c(p);
;   xcd_barrier(xb);
;   phase3(p);
;   xcd_barrier(xb);
;   phase4(p);
;   if (gridDim.x != 256) {
;     xcd_barrier(xb);
;     phase5(p);
;   }
; }
amdhsa.kernels:
  - .agpr_count:     0
    .args:
      - .offset:         0
        .size:           280
        .value_kind:     by_value
      - .offset:         280
        .size:           4
        .value_kind:     hidden_block_count_x
      - .offset:         284
        .size:           4
        .value_kind:     hidden_block_count_y
      - .offset:         288
        .size:           4
        .value_kind:     hidden_block_count_z
      - .offset:         292
        .size:           2
        .value_kind:     hidden_group_size_x
      - .offset:         294
        .size:           2
        .value_kind:     hidden_group_size_y
      - .offset:         296
        .size:           2
        .value_kind:     hidden_group_size_z
      - .offset:         298
        .size:           2
        .value_kind:     hidden_remainder_x
      - .offset:         300
        .size:           2
        .value_kind:     hidden_remainder_y
      - .offset:         302
        .size:           2
        .value_kind:     hidden_remainder_z
      - .offset:         320
        .size:           8
        .value_kind:     hidden_global_offset_x
      - .offset:         328
        .size:           8
        .value_kind:     hidden_global_offset_y
      - .offset:         336
        .size:           8
        .value_kind:     hidden_global_offset_z
      - .offset:         344
        .size:           2
        .value_kind:     hidden_grid_dims
      - .offset:         368
        .size:           8
        .value_kind:     hidden_multigrid_sync_arg
    .group_segment_fixed_size: 163840
    .kernarg_segment_align: 8
    .kernarg_segment_size: 536
    .language:       OpenCL C
    .language_version:
      - 2
      - 0
    .max_flat_workgroup_size: 512
    .name:           _Z14fwd_megakernel6Params
    .private_segment_fixed_size: 0
    .sgpr_count:     106
    .sgpr_spill_count: 12
    .symbol:         _Z14fwd_megakernel6Params.kd
    .uniform_work_group_size: 1
    .uses_dynamic_stack: false
    .vgpr_count:     256
    .vgpr_spill_count: 0
    .wavefront_size: 64
